# PEER pass index: half of each XCD's token blocks from its own GEMM panels, half from the XCD four away; on top of v076
# baseline (speedup 1.0000x reference)
.LBB0_13:
	v_readlane_b32 s0, v254, 16
	s_add_i32 s10, s0, -2
	s_and_b32 s0, s10, 0xff
	s_mul_i32 s0, s0, 37
	s_lshr_b32 s0, s0, 8
	s_sub_i32 s1, s10, s0
	s_bfe_u32 s1, s1, 0x70001
	s_add_i32 s1, s1, s0
	s_bfe_u32 s92, s1, 0x60002
	s_mul_i32 s0, s92, 7
	s_sub_i32 s0, s10, s0
	s_and_b32 s0, s0, 0xff
	v_writelane_b32 v254, s0, 18
	s_cmp_lt_i32 s0, 3
	s_mov_b64 s[0:1], -1
	s_cbranch_scc1 .LBB0_403
	v_readlane_b32 s0, v254, 18
	s_and_b32 s2, 0xffff, s0
	v_writelane_b32 v254, s91, 19
	s_cmp_lt_i32 s2, 4
	s_mov_b64 s[0:1], -1
	v_writelane_b32 v254, s92, 20
	s_cbranch_scc1 .LBB0_346
	s_cmp_lt_i32 s2, 5
	s_cbranch_scc1 .LBB0_207
	s_cmp_lg_u32 s2, 5
	s_cbranch_scc0 .LBB0_161
	v_readlane_b32 s0, v254, 3
	v_readlane_b32 s1, v254, 4
	v_readlane_b32 s2, v254, 5
	v_readlane_b32 s3, v254, 6
	s_mov_b64 s[14:15], s[0:1]
	s_mov_b64 s[0:1], s[2:3]
	s_mov_b32 s57, s61
	v_writelane_b32 v254, s0, 23
	v_mov_b32_e32 v133, v0
	s_nop 0
	v_writelane_b32 v254, s1, 24
	s_nop 0
	v_readlane_b32 s0, v254, 0
	s_mov_b32 s16, s0
	v_readlane_b32 s0, v254, 12
	v_readlane_b32 s1, v254, 13
	s_load_dword s0, s[0:1], 0x0
	s_waitcnt lgkmcnt(0)
	s_cmp_eq_u32 s0, 0x100
	s_cbranch_scc0 .Lpeer_noperm
	s_lshr_b32 s1, s16, 3
	s_and_b32 s2, s1, 1
	s_lshl_b32 s2, s2, 2
	s_add_i32 s16, s16, s2
	s_and_b32 s16, s16, 7
	s_lshl_b32 s16, s16, 5
	s_or_b32 s16, s16, s1
